# speedup vs baseline: 1.0073x; 1.0017x over previous
; __device__ __forceinline__ void attn_phase(char* shm, const Params& p, const u16* __restrict__ qb, const u16* __restrict__ kb,
;                                            const u16* __restrict__ vT, u16* __restrict__ attn) {
;     ...
;     const int r = it >> 8, vb = it & 255, xcd = vb & 7, idx = vb >> 3;
;     int h, S, tok0, qblk;
;     if (r < 2) { int bh = r * 16 + xcd * 2 + (idx >> 4); h = bh & 7; S = 4096; tok0 = T_PROMPT + (bh >> 3) * 4096; qblk = idx & 15; }
;     else { int pr = (r - 2) * 32 + xcd * 4 + (idx >> 3); h = pr & 7; S = 2048; tok0 = (pr >> 3) * 2048; qblk = idx & 7; }
.LBB0_293:
	s_ashr_i32 s38, s19, 8
	s_and_b32 s39, s19, 7
	s_bfe_u32 s41, s19, 0x50003
	s_cmp_gt_i32 s38, 1
	s_mov_b64 s[36:37], -1
	s_cbranch_scc0 .LBB0_295
	s_lshl_b32 s36, s39, 10
	s_lshl_b32 s37, s38, 13
	s_lshl_b32 s0, s39, 2
	s_or_b32 s36, s37, s36
	s_lshr_b32 s37, s41, 3
	s_and_b32 s0, s0, 4
	s_addk_i32 s36, 0xc000
	s_or_b32 s0, s0, s37
	s_lshl_b32 s37, s38, 1
	s_add_i32 s0, s0, s37
	s_add_i32 s0, s0, 4
	s_and_b32 s0, s0, 7
	s_and_b32 s40, s36, 0x7ffff800
	s_mov_b64 s[36:37], 0
.LBB0_295:
	s_andn2_b64 vcc, exec, s[36:37]
	s_cbranch_vccnz .LBB0_297
	s_lshl_b32 s0, s39, 1
	s_lshr_b32 s36, s41, 4
	s_and_b32 s0, s0, 6
	s_lshl_b32 s37, s39, 10
	s_or_b32 s0, s0, s36
	s_lshl_b32 s36, s38, 2
	s_add_i32 s0, s0, s36
	s_and_b32 s0, s0, 7
	s_lshl_b32 s36, s38, 13
	s_and_b32 s37, s37, 0x1000
	s_or_b32 s36, s36, s37
	s_movk_i32 s44, 0x1000
	s_add_i32 s40, s36, 0x8000
	s_mov_b32 s36, 15
	s_branch .LBB0_298

; #define SCHED() __builtin_amdgcn_sched_barrier(0)
; #define DSR(dst, addr, off) asm volatile("ds_read_b128 %0, %1 offset:%2" : "=&v"(dst) : "v"(addr), "n"(off) : "memory")
; #define LGKM(n) asm volatile("s_waitcnt lgkmcnt(%0)" ::"n"(n) : "memory")
; #define DSR(dst, addr, off) asm volatile("ds_read_b128 %0, %1 offset:%2" : "=&v"(dst) : "v"(addr), "n"(off) : "memory")
; #define LGKM(n) asm volatile("s_waitcnt lgkmcnt(%0)" ::"n"(n) : "memory")
; __device__ __forceinline__ void attn_phase(char* shm, const Params& p, const u16* __restrict__ qb, const u16* __restrict__ kb,
;                                            const u16* __restrict__ vT, u16* __restrict__ attn) {
;     ...
;         const float df = (float)(kt * 64 + u * 32 + 4 * hh - qpos);
;         bf16x8 P[2][2];
;         bf16x8 kf[2], qf[2];
;         DSR(kf[0], kb_ + kL0, u * 8192); DSR(qf[0], qaddr, 0);
; #pragma unroll
;         for (int c = 0; c < 2; ++c) {
;           f32x16 Sx;
; #pragma unroll
;           for (int i = 0; i < 16; ++i) Sx[i] = -sl2 * fabsf(df + (float)((i & 3) + 8 * (i >> 2)));
; #pragma unroll
;           for (int ks = 0; ks < 4; ++ks) {
;             const int f = c * 4 + ks;
;             if (f < 7) {
;               DSR(kf[(f + 1) & 1], kb_ + (kL0 ^ ((((f + 1) >> 2) * 8 + ((f + 1) & 3) * 2) << 4)), u * 8192);
;               DSR(qf[(f + 1) & 1], qaddr, (f + 1) * 1024);
;               LGKM(2);
;             } else LGKM(0);
;             SCHED();
;             Sx = __builtin_amdgcn_mfma_f32_32x32x16_bf16(kf[f & 1], qf[f & 1], Sx, 0, 0, 0);
;             SCHED();
;           }
;           float pv[16];
; #pragma unroll
;           for (int i = 0; i < 16; ++i) { pv[i] = __builtin_amdgcn_exp2f(Sx[i]); lsum[c] += pv[i]; }
; #pragma unroll
;           for (int a = 0; a < 2; ++a) {
;             i32x4 t4;
; #pragma unroll
;             for (int i = 0; i < 4; ++i) t4[i] = pk_bf16(pv[a * 8 + 2 * i], pv[a * 8 + 2 * i + 1]);
;             P[c][a] = __builtin_bit_cast(bf16x8, t4);
;           }
;         }
.LBB0_299:
	v_cvt_f32_i32_e32 v128, v205
	v_add_u32_e32 v160, s44, v188
	ds_read_b128 v[206:209], v160 offset:0
	ds_read_b128 v[210:213], v185 offset:0
	v_add_u32_e32 v214, s44, v190
	ds_read_b128 v[218:221], v214 offset:0
	ds_read_b128 v[222:225], v185 offset:0x400
	v_add_u32_e32 v215, s44, v191
	ds_read_b128 v[242:245], v215 offset:0
	ds_read_b128 v[246:249], v185 offset:0x800
	v_add_f32_e32 v129, 1.0, v128
	v_pk_add_f32 v[130:131], v[128:129], s[12:13] op_sel_hi:[0,1]
	v_pk_add_f32 v[132:133], v[128:129], s[14:15] op_sel_hi:[0,1]
	v_pk_add_f32 v[134:135], v[128:129], s[20:21] op_sel_hi:[0,1]
	v_pk_add_f32 v[136:137], v[128:129], s[22:23] op_sel_hi:[0,1]
	v_pk_add_f32 v[138:139], v[128:129], s[24:25] op_sel_hi:[0,1]
	v_pk_add_f32 v[140:141], v[128:129], s[26:27] op_sel_hi:[0,1]
	v_pk_add_f32 v[142:143], v[128:129], s[28:29] op_sel_hi:[0,1]
	v_and_b32_e32 v131, 0x7fffffff, v131
	v_and_b32_e32 v130, 0x7fffffff, v130
	v_and_b32_e32 v133, 0x7fffffff, v133
	v_and_b32_e32 v132, 0x7fffffff, v132
	v_and_b32_e32 v135, 0x7fffffff, v135
	v_and_b32_e32 v134, 0x7fffffff, v134
	v_and_b32_e32 v137, 0x7fffffff, v137
	v_and_b32_e32 v136, 0x7fffffff, v136
	v_and_b32_e32 v139, 0x7fffffff, v139
	v_and_b32_e32 v138, 0x7fffffff, v138
	v_and_b32_e32 v141, 0x7fffffff, v141
	v_and_b32_e32 v140, 0x7fffffff, v140
	v_and_b32_e32 v143, 0x7fffffff, v143
	v_and_b32_e32 v142, 0x7fffffff, v142
	v_and_b32_e32 v128, 0x7fffffff, v128
	v_and_b32_e32 v129, 0x7fffffff, v129
	s_add_i32 s0, s44, 0x4000
	v_pk_mul_f32 v[142:143], v[178:179], v[142:143]
	v_pk_mul_f32 v[140:141], v[178:179], v[140:141]
	v_pk_mul_f32 v[138:139], v[178:179], v[138:139]
	v_pk_mul_f32 v[136:137], v[178:179], v[136:137]
	v_pk_mul_f32 v[134:135], v[178:179], v[134:135]
	v_pk_mul_f32 v[132:133], v[178:179], v[132:133]
	v_pk_mul_f32 v[130:131], v[178:179], v[130:131]
	v_pk_mul_f32 v[128:129], v[170:171], v[128:129]
	s_nop 1
	s_waitcnt lgkmcnt(4)
	v_readfirstlane_b32 s88, v128
	s_cmp_gt_u32 s88, 0xc35c0000
	s_cselect_b32 s89, 1, 0
	v_mfma_f32_32x32x16_bf16 v[144:159], v[206:209], v[210:213], v[128:143]
	v_add_u32_e32 v226, s44, v192
	ds_read_b128 v[206:209], v226 offset:0
	ds_read_b128 v[210:213], v185 offset:0xc00
	s_waitcnt lgkmcnt(4)
	v_mfma_f32_32x32x16_bf16 v[144:159], v[218:221], v[222:225], v[144:159]
	v_add_u32_e32 v227, s44, v193
	ds_read_b128 v[218:221], v227 offset:0
	ds_read_b128 v[222:225], v185 offset:0x1000
	s_waitcnt lgkmcnt(4)
	v_mfma_f32_32x32x16_bf16 v[144:159], v[242:245], v[246:249], v[144:159]
	v_add_u32_e32 v229, s44, v194
	ds_read_b128 v[242:245], v229 offset:0
	ds_read_b128 v[246:249], v185 offset:0x1400
	s_waitcnt lgkmcnt(4)
	v_mfma_f32_32x32x16_bf16 v[144:159], v[206:209], v[210:213], v[144:159]
	v_add_u32_e32 v230, s44, v195
	ds_read_b128 v[206:209], v230 offset:0
	ds_read_b128 v[210:213], v185 offset:0x1800
	s_nop 11
	s_cmp_eq_u32 s89, 0
	s_cbranch_scc1 .Lattn_exp_normal_0_0
	v_max3_f32 v240, v144, v145, v146
	v_max3_f32 v240, v240, v147, v148
	v_max3_f32 v240, v240, v149, v150
	v_max3_f32 v240, v240, v151, v152
	v_max3_f32 v240, v240, v153, v154
	v_max3_f32 v240, v240, v155, v156
	v_max3_f32 v240, v240, v157, v158
	v_max_f32_e32 v240, v240, v159
	v_cmp_ngt_f32_e32 vcc, 0xc3180000, v240
	s_and_b64 vcc, exec, vcc
	s_cbranch_vccnz .Lattn_exp_normal_0_0
	v_mov_b32_e32 v144, 0
	v_mov_b32_e32 v145, 0
	v_mov_b32_e32 v146, 0
	v_mov_b32_e32 v147, 0
	v_mov_b32_e32 v148, 0
	v_mov_b32_e32 v149, 0
	v_mov_b32_e32 v150, 0
	v_mov_b32_e32 v151, 0
	s_branch .Lattn_exp_done_0_0
.Lattn_exp_normal_0_0:
	v_exp_f32_e32 v144, v144
	v_exp_f32_e32 v145, v145
	v_exp_f32_e32 v146, v146
	v_exp_f32_e32 v147, v147
	v_add_f32_e32 v181, v181, v144
	v_exp_f32_e32 v148, v148
	v_add_f32_e32 v181, v145, v181
	v_exp_f32_e32 v149, v149
	v_add_f32_e32 v181, v146, v181
	v_exp_f32_e32 v150, v150
	v_add_f32_e32 v181, v147, v181
	v_exp_f32_e32 v151, v151
	v_add_f32_e32 v181, v148, v181
	v_exp_f32_e32 v152, v152
	v_add_f32_e32 v181, v149, v181
	v_exp_f32_e32 v153, v153
	v_add_f32_e32 v181, v150, v181
	v_exp_f32_e32 v154, v154
	v_add_f32_e32 v181, v151, v181
	v_exp_f32_e32 v155, v155
	v_add_f32_e32 v181, v152, v181
	v_exp_f32_e32 v156, v156
	v_add_f32_e32 v181, v153, v181
	v_exp_f32_e32 v157, v157
	v_add_f32_e32 v181, v154, v181
	v_exp_f32_e32 v158, v158
	v_add_f32_e32 v181, v155, v181
	v_exp_f32_e32 v159, v159
	v_add_f32_e32 v181, v156, v181
	v_add_f32_e32 v181, v157, v181
	v_add_f32_e32 v181, v158, v181
	v_cvt_pk_bf16_f32 v144, v144, v145
	v_cvt_pk_bf16_f32 v145, v146, v147
	v_cvt_pk_bf16_f32 v146, v148, v149
	v_cvt_pk_bf16_f32 v148, v152, v153
	v_cvt_pk_bf16_f32 v149, v154, v155
	v_add_f32_e32 v181, v159, v181
	v_cvt_pk_bf16_f32 v147, v150, v151
	v_cvt_pk_bf16_f32 v150, v156, v157
	v_cvt_pk_bf16_f32 v151, v158, v159
.Lattn_exp_done_0_0:
	s_waitcnt lgkmcnt(4)
	v_mfma_f32_32x32x16_bf16 v[128:143], v[218:221], v[222:225], v[128:143]
	v_add_u32_e32 v232, s44, v196
	ds_read_b128 v[218:221], v232 offset:0
	ds_read_b128 v[222:225], v185 offset:0x1c00
	s_waitcnt lgkmcnt(4)
	v_mfma_f32_32x32x16_bf16 v[128:143], v[242:245], v[246:249], v[128:143]
	s_waitcnt lgkmcnt(2)
	v_mfma_f32_32x32x16_bf16 v[128:143], v[206:209], v[210:213], v[128:143]
	s_waitcnt lgkmcnt(0)
	v_mfma_f32_32x32x16_bf16 v[128:143], v[218:221], v[222:225], v[128:143]
	s_nop 11
	s_cmp_eq_u32 s89, 0
	s_cbranch_scc1 .Lattn_exp_normal_0_1
	v_max3_f32 v240, v128, v129, v130
	v_max3_f32 v240, v240, v131, v132
	v_max3_f32 v240, v240, v133, v134
	v_max3_f32 v240, v240, v135, v136
	v_max3_f32 v240, v240, v137, v138
	v_max3_f32 v240, v240, v139, v140
	v_max3_f32 v240, v240, v141, v142
	v_max_f32_e32 v240, v240, v143
	v_cmp_ngt_f32_e32 vcc, 0xc3180000, v240
	s_and_b64 vcc, exec, vcc
	s_cbranch_vccnz .Lattn_exp_normal_0_1
	v_add_u32_e32 v152, s0, v189
	ds_read_b128 v[136:139], v152 offset:0
	ds_read_b128 v[140:143], v152 offset:0x1000
	v_mov_b32_e32 v128, 0
	v_mov_b32_e32 v129, 0
	v_mov_b32_e32 v130, 0
	v_mov_b32_e32 v131, 0
	v_mov_b32_e32 v132, 0
	v_mov_b32_e32 v133, 0
	v_mov_b32_e32 v134, 0
	v_mov_b32_e32 v135, 0
	s_branch .Lattn_exp_done_0_1
; #define SCHED() __builtin_amdgcn_sched_barrier(0)
; #define DSR(dst, addr, off) asm volatile("ds_read_b128 %0, %1 offset:%2" : "=&v"(dst) : "v"(addr), "n"(off) : "memory")
; __device__ __forceinline__ void attn_phase(char* shm, const Params& p, const u16* __restrict__ qb, const u16* __restrict__ kb,
;                                            const u16* __restrict__ vT, u16* __restrict__ attn) {
;     ...
;         const float df = (float)(kt * 64 + u * 32 + 4 * hh - qpos);
;         bf16x8 P[2][2];
;         bf16x8 kf[2], qf[2];
;         DSR(kf[0], kb_ + kL0, u * 8192); DSR(qf[0], qaddr, 0);
; #pragma unroll
;         for (int c = 0; c < 2; ++c) {
;           f32x16 Sx;
; #pragma unroll
;           for (int i = 0; i < 16; ++i) Sx[i] = -sl2 * fabsf(df + (float)((i & 3) + 8 * (i >> 2)));
; #pragma unroll
;           for (int ks = 0; ks < 4; ++ks) {
;             const int f = c * 4 + ks;
;             if (f < 7) {
;               DSR(kf[(f + 1) & 1], kb_ + (kL0 ^ ((((f + 1) >> 2) * 8 + ((f + 1) & 3) * 2) << 4)), u * 8192);
;               DSR(qf[(f + 1) & 1], qaddr, (f + 1) * 1024);
;               LGKM(2);
;             } else LGKM(0);
;             SCHED();
;             Sx = __builtin_amdgcn_mfma_f32_32x32x16_bf16(kf[f & 1], qf[f & 1], Sx, 0, 0, 0);
;             SCHED();
;           }
;           float pv[16];
; #pragma unroll
;           for (int i = 0; i < 16; ++i) { pv[i] = __builtin_amdgcn_exp2f(Sx[i]); lsum[c] += pv[i]; }
; #pragma unroll
;           for (int a = 0; a < 2; ++a) {
;             i32x4 t4;
; #pragma unroll
;             for (int i = 0; i < 4; ++i) t4[i] = pk_bf16(pv[a * 8 + 2 * i], pv[a * 8 + 2 * i + 1]);
;             P[c][a] = __builtin_bit_cast(bf16x8, t4);
;           }
;         }
;         bf16x8 vf[2];
;         DSR(vf[0], vb_ + (vM0 ^ ((u * 4) << 4)), 0);
; #pragma unroll
;         for (int g = 0; g < 8; ++g) {
;           const int a = g >> 2, t = g & 3;
;           if (g < 7) { DSR(vf[(g + 1) & 1], vb_ + (vM0 ^ ((u * 4 + ((g + 1) >> 2) * 2) << 4)), ((g + 1) & 3) * 4096); LGKM(1); }
;           else LGKM(0);
;           SCHED();
;           O[0][t] = __builtin_amdgcn_mfma_f32_32x32x16_bf16(vf[g & 1], P[0][a], O[0][t], 0, 0, 0);
;           O[1][t] = __builtin_amdgcn_mfma_f32_32x32x16_bf16(vf[g & 1], P[1][a], O[1][t], 0, 0, 0);
;           SCHED();
;         }
.Lattn_exp_normal_0_1:
	v_exp_f32_e32 v128, v128
	v_exp_f32_e32 v129, v129
	v_exp_f32_e32 v130, v130
	v_exp_f32_e32 v131, v131
	v_add_f32_e32 v152, v180, v128
	v_exp_f32_e32 v132, v132
	v_add_f32_e32 v152, v129, v152
	v_exp_f32_e32 v133, v133
	v_add_f32_e32 v152, v130, v152
	v_exp_f32_e32 v134, v134
	v_add_f32_e32 v152, v131, v152
	v_exp_f32_e32 v135, v135
	v_add_f32_e32 v152, v132, v152
	v_exp_f32_e32 v136, v136
	v_add_f32_e32 v152, v133, v152
	v_exp_f32_e32 v137, v137
	v_add_f32_e32 v152, v134, v152
	v_exp_f32_e32 v138, v138
	v_add_f32_e32 v152, v135, v152
	v_exp_f32_e32 v139, v139
	v_add_f32_e32 v152, v136, v152
	v_exp_f32_e32 v140, v140
	v_add_f32_e32 v152, v137, v152
	v_exp_f32_e32 v141, v141
	v_add_f32_e32 v152, v138, v152
	v_exp_f32_e32 v142, v142
	v_add_f32_e32 v152, v139, v152
	v_exp_f32_e32 v143, v143
	v_add_f32_e32 v152, v140, v152
	v_add_f32_e32 v152, v141, v152
	v_add_f32_e32 v152, v142, v152
	v_add_f32_e32 v180, v143, v152
	v_cvt_pk_bf16_f32 v128, v128, v129
	v_cvt_pk_bf16_f32 v129, v130, v131
	v_cvt_pk_bf16_f32 v130, v132, v133
	v_cvt_pk_bf16_f32 v132, v136, v137
	v_cvt_pk_bf16_f32 v133, v138, v139
	v_add_u32_e32 v152, s0, v189
	ds_read_b128 v[136:139], v152 offset:0
	v_cvt_pk_bf16_f32 v131, v134, v135
	v_cvt_pk_bf16_f32 v134, v140, v141
	v_cvt_pk_bf16_f32 v135, v142, v143
	ds_read_b128 v[140:143], v152 offset:0x1000
.Lattn_exp_done_0_1:
	s_waitcnt lgkmcnt(1)
	v_or3_b32 v240, v128, v129, v130
	v_or3_b32 v240, v240, v131, v132
	v_or3_b32 v240, v240, v133, v134
	v_or3_b32 v240, v240, v135, v144
	v_or3_b32 v240, v240, v145, v146
	v_or3_b32 v240, v240, v147, v148
	v_or3_b32 v240, v240, v149, v150
	v_or_b32_e32 v240, v240, v151
	v_cmp_ne_u32_e32 vcc, 0, v240
	s_and_b64 vcc, exec, vcc
	s_cbranch_vccz .Lattn_pv_zero_0
	v_mfma_f32_32x32x16_bf16 v[112:127], v[136:139], v[144:147], v[112:127]
	v_mfma_f32_32x32x16_bf16 v[96:111], v[136:139], v[128:131], v[96:111]
	ds_read_b128 v[136:139], v152 offset:0x2000
	s_waitcnt lgkmcnt(1)
	v_mfma_f32_32x32x16_bf16 v[80:95], v[140:143], v[144:147], v[80:95]
	v_mfma_f32_32x32x16_bf16 v[64:79], v[140:143], v[128:131], v[64:79]
	ds_read_b128 v[140:143], v152 offset:0x3000
	s_waitcnt lgkmcnt(1)
	v_mfma_f32_32x32x16_bf16 v[48:63], v[136:139], v[144:147], v[48:63]
	v_mfma_f32_32x32x16_bf16 v[16:31], v[136:139], v[128:131], v[16:31]
	v_add_u32_e32 v152, s0, v197
	ds_read_b128 v[136:139], v152 offset:0
	s_waitcnt lgkmcnt(1)
	v_mfma_f32_32x32x16_bf16 v[32:47], v[140:143], v[144:147], v[32:47]
	v_mfma_f32_32x32x16_bf16 v[0:15], v[140:143], v[128:131], v[0:15]
	ds_read_b128 v[128:131], v152 offset:0x1000
	s_waitcnt lgkmcnt(1)
	v_mfma_f32_32x32x16_bf16 v[112:127], v[136:139], v[148:151], v[112:127]
	v_mfma_f32_32x32x16_bf16 v[96:111], v[136:139], v[132:135], v[96:111]
	ds_read_b128 v[136:139], v152 offset:0x2000
	s_waitcnt lgkmcnt(1)
	v_mfma_f32_32x32x16_bf16 v[80:95], v[128:131], v[148:151], v[80:95]
	v_mfma_f32_32x32x16_bf16 v[64:79], v[128:131], v[132:135], v[64:79]
	ds_read_b128 v[128:131], v152 offset:0x3000
	s_waitcnt lgkmcnt(1)
	v_mfma_f32_32x32x16_bf16 v[48:63], v[136:139], v[148:151], v[48:63]
	v_mfma_f32_32x32x16_bf16 v[16:31], v[136:139], v[132:135], v[16:31]
	s_waitcnt lgkmcnt(0)
	v_mfma_f32_32x32x16_bf16 v[32:47], v[128:131], v[148:151], v[32:47]
	v_mfma_f32_32x32x16_bf16 v[0:15], v[128:131], v[132:135], v[0:15]
.Lattn_pv_zero_0:
	s_waitcnt lgkmcnt(0)
	v_add_u32_e32 v128, 32, v205
	v_cvt_f32_i32_e32 v128, v128
	ds_read_b128 v[206:209], v160 offset:0x2000
	ds_read_b128 v[210:213], v185 offset:0
	ds_read_b128 v[218:221], v214 offset:0x2000
	ds_read_b128 v[222:225], v185 offset:0x400
	ds_read_b128 v[242:245], v215 offset:0x2000
	ds_read_b128 v[246:249], v185 offset:0x800
	v_add_f32_e32 v129, 1.0, v128
	v_pk_add_f32 v[130:131], v[128:129], s[12:13] op_sel_hi:[0,1]
	v_pk_add_f32 v[132:133], v[128:129], s[14:15] op_sel_hi:[0,1]
	v_pk_add_f32 v[134:135], v[128:129], s[20:21] op_sel_hi:[0,1]
	v_pk_add_f32 v[136:137], v[128:129], s[22:23] op_sel_hi:[0,1]
	v_pk_add_f32 v[138:139], v[128:129], s[24:25] op_sel_hi:[0,1]
	v_pk_add_f32 v[140:141], v[128:129], s[26:27] op_sel_hi:[0,1]
	v_pk_add_f32 v[142:143], v[128:129], s[28:29] op_sel_hi:[0,1]
	v_and_b32_e32 v131, 0x7fffffff, v131
	v_and_b32_e32 v130, 0x7fffffff, v130
	v_and_b32_e32 v133, 0x7fffffff, v133
	v_and_b32_e32 v132, 0x7fffffff, v132
	v_and_b32_e32 v135, 0x7fffffff, v135
	v_and_b32_e32 v134, 0x7fffffff, v134
	v_and_b32_e32 v137, 0x7fffffff, v137
	v_and_b32_e32 v136, 0x7fffffff, v136
	v_and_b32_e32 v139, 0x7fffffff, v139
	v_and_b32_e32 v138, 0x7fffffff, v138
	v_and_b32_e32 v141, 0x7fffffff, v141
	v_and_b32_e32 v140, 0x7fffffff, v140
	v_and_b32_e32 v143, 0x7fffffff, v143
	v_and_b32_e32 v142, 0x7fffffff, v142
	v_and_b32_e32 v128, 0x7fffffff, v128
	v_and_b32_e32 v129, 0x7fffffff, v129
	v_pk_mul_f32 v[142:143], v[178:179], v[142:143]
	v_pk_mul_f32 v[140:141], v[178:179], v[140:141]
	v_pk_mul_f32 v[138:139], v[178:179], v[138:139]
	v_pk_mul_f32 v[136:137], v[178:179], v[136:137]
	v_pk_mul_f32 v[134:135], v[178:179], v[134:135]
	v_pk_mul_f32 v[132:133], v[178:179], v[132:133]
	v_pk_mul_f32 v[130:131], v[178:179], v[130:131]
	v_pk_mul_f32 v[128:129], v[170:171], v[128:129]
	s_nop 1
	s_waitcnt lgkmcnt(4)
	v_readfirstlane_b32 s88, v128
	s_cmp_gt_u32 s88, 0xc35c0000
	s_cselect_b32 s89, 1, 0
	v_mfma_f32_32x32x16_bf16 v[144:159], v[206:209], v[210:213], v[128:143]
	ds_read_b128 v[206:209], v226 offset:0x2000
	ds_read_b128 v[210:213], v185 offset:0xc00
	s_waitcnt lgkmcnt(4)
	v_mfma_f32_32x32x16_bf16 v[144:159], v[218:221], v[222:225], v[144:159]
	ds_read_b128 v[218:221], v227 offset:0x2000
	ds_read_b128 v[222:225], v185 offset:0x1000
	s_waitcnt lgkmcnt(4)
	v_mfma_f32_32x32x16_bf16 v[144:159], v[242:245], v[246:249], v[144:159]
	ds_read_b128 v[242:245], v229 offset:0x2000
	ds_read_b128 v[246:249], v185 offset:0x1400
	s_waitcnt lgkmcnt(4)
	v_mfma_f32_32x32x16_bf16 v[144:159], v[206:209], v[210:213], v[144:159]
	ds_read_b128 v[206:209], v230 offset:0x2000
	ds_read_b128 v[210:213], v185 offset:0x1800
	s_nop 11
	s_cmp_eq_u32 s89, 0
	s_cbranch_scc1 .Lattn_exp_normal_1_0
	v_max3_f32 v240, v144, v145, v146
	v_max3_f32 v240, v240, v147, v148
	v_max3_f32 v240, v240, v149, v150
	v_max3_f32 v240, v240, v151, v152
	v_max3_f32 v240, v240, v153, v154
	v_max3_f32 v240, v240, v155, v156
	v_max3_f32 v240, v240, v157, v158
	v_max_f32_e32 v240, v240, v159
	v_cmp_ngt_f32_e32 vcc, 0xc3180000, v240
	s_and_b64 vcc, exec, vcc
	s_cbranch_vccnz .Lattn_exp_normal_1_0
	v_mov_b32_e32 v144, 0
	v_mov_b32_e32 v145, 0
	v_mov_b32_e32 v146, 0
	v_mov_b32_e32 v147, 0
	v_mov_b32_e32 v148, 0
	v_mov_b32_e32 v149, 0
	v_mov_b32_e32 v150, 0
	v_mov_b32_e32 v151, 0
	s_branch .Lattn_exp_done_1_0

; #define SCHED() __builtin_amdgcn_sched_barrier(0)
; #define DSR(dst, addr, off) asm volatile("ds_read_b128 %0, %1 offset:%2" : "=&v"(dst) : "v"(addr), "n"(off) : "memory")
; #define LGKM(n) asm volatile("s_waitcnt lgkmcnt(%0)" ::"n"(n) : "memory")
; #define DSR(dst, addr, off) asm volatile("ds_read_b128 %0, %1 offset:%2" : "=&v"(dst) : "v"(addr), "n"(off) : "memory")
; #define LGKM(n) asm volatile("s_waitcnt lgkmcnt(%0)" ::"n"(n) : "memory")
; __device__ __forceinline__ void attn_phase(char* shm, const Params& p, const u16* __restrict__ qb, const u16* __restrict__ kb,
;                                            const u16* __restrict__ vT, u16* __restrict__ attn) {
;     ...
;           for (int i = 0; i < 16; ++i) Sx[i] = -sl2 * fabsf(df + (float)((i & 3) + 8 * (i >> 2)));
; #pragma unroll
;           for (int ks = 0; ks < 4; ++ks) {
;             const int f = c * 4 + ks;
;             if (f < 7) {
;               DSR(kf[(f + 1) & 1], kb_ + (kL0 ^ ((((f + 1) >> 2) * 8 + ((f + 1) & 3) * 2) << 4)), u * 8192);
;               DSR(qf[(f + 1) & 1], qaddr, (f + 1) * 1024);
;               LGKM(2);
;             } else LGKM(0);
;             SCHED();
;             Sx = __builtin_amdgcn_mfma_f32_32x32x16_bf16(kf[f & 1], qf[f & 1], Sx, 0, 0, 0);
;             SCHED();
;           }
;           float pv[16];
; #pragma unroll
;           for (int i = 0; i < 16; ++i) { pv[i] = __builtin_amdgcn_exp2f(Sx[i]); lsum[c] += pv[i]; }
; #pragma unroll
;           for (int a = 0; a < 2; ++a) {
;             i32x4 t4;
; #pragma unroll
;             for (int i = 0; i < 4; ++i) t4[i] = pk_bf16(pv[a * 8 + 2 * i], pv[a * 8 + 2 * i + 1]);
;             P[c][a] = __builtin_bit_cast(bf16x8, t4);
;           }
;         }
;         bf16x8 vf[2];
;         DSR(vf[0], vb_ + (vM0 ^ ((u * 4) << 4)), 0);
; #pragma unroll
;         for (int g = 0; g < 8; ++g) {
;           const int a = g >> 2, t = g & 3;
;           if (g < 7) { DSR(vf[(g + 1) & 1], vb_ + (vM0 ^ ((u * 4 + ((g + 1) >> 2) * 2) << 4)), ((g + 1) & 3) * 4096); LGKM(1); }
;           else LGKM(0);
;           SCHED();
;           O[0][t] = __builtin_amdgcn_mfma_f32_32x32x16_bf16(vf[g & 1], P[0][a], O[0][t], 0, 0, 0);
;           O[1][t] = __builtin_amdgcn_mfma_f32_32x32x16_bf16(vf[g & 1], P[1][a], O[1][t], 0, 0, 0);
;           SCHED();
;         }
.Lattn_exp_done_1_0:
	s_waitcnt lgkmcnt(4)
	v_mfma_f32_32x32x16_bf16 v[128:143], v[218:221], v[222:225], v[128:143]
	ds_read_b128 v[218:221], v232 offset:0x2000
	ds_read_b128 v[222:225], v185 offset:0x1c00
	s_waitcnt lgkmcnt(4)
	v_mfma_f32_32x32x16_bf16 v[128:143], v[242:245], v[246:249], v[128:143]
	s_waitcnt lgkmcnt(2)
	v_mfma_f32_32x32x16_bf16 v[128:143], v[206:209], v[210:213], v[128:143]
	s_waitcnt lgkmcnt(0)
	v_mfma_f32_32x32x16_bf16 v[128:143], v[218:221], v[222:225], v[128:143]
	s_nop 11
	s_cmp_eq_u32 s89, 0
	s_cbranch_scc1 .Lattn_exp_normal_1_1
	v_max3_f32 v240, v128, v129, v130
	v_max3_f32 v240, v240, v131, v132
	v_max3_f32 v240, v240, v133, v134
	v_max3_f32 v240, v240, v135, v136
	v_max3_f32 v240, v240, v137, v138
	v_max3_f32 v240, v240, v139, v140
	v_max3_f32 v240, v240, v141, v142
	v_max_f32_e32 v240, v240, v143
	v_cmp_ngt_f32_e32 vcc, 0xc3180000, v240
	s_and_b64 vcc, exec, vcc
	s_cbranch_vccnz .Lattn_exp_normal_1_1
	v_add_u32_e32 v152, s0, v198
	ds_read_b128 v[136:139], v152 offset:0
	ds_read_b128 v[140:143], v152 offset:0x1000
	v_mov_b32_e32 v128, 0
	v_mov_b32_e32 v129, 0
	v_mov_b32_e32 v130, 0
	v_mov_b32_e32 v131, 0
	v_mov_b32_e32 v132, 0
	v_mov_b32_e32 v133, 0
	v_mov_b32_e32 v134, 0
	v_mov_b32_e32 v135, 0
	s_branch .Lattn_exp_done_1_1
.Lattn_exp_normal_1_1:
	v_exp_f32_e32 v128, v128
	v_exp_f32_e32 v129, v129
	v_exp_f32_e32 v130, v130
	v_exp_f32_e32 v131, v131
	v_add_f32_e32 v152, v180, v128
	v_exp_f32_e32 v132, v132
	v_add_f32_e32 v152, v129, v152
	v_exp_f32_e32 v133, v133
	v_add_f32_e32 v152, v130, v152
	v_exp_f32_e32 v134, v134
	v_add_f32_e32 v152, v131, v152
	v_exp_f32_e32 v135, v135
	v_add_f32_e32 v152, v132, v152
	v_exp_f32_e32 v136, v136
	v_add_f32_e32 v152, v133, v152
	v_exp_f32_e32 v137, v137
	v_add_f32_e32 v152, v134, v152
	v_exp_f32_e32 v138, v138
	v_add_f32_e32 v152, v135, v152
	v_exp_f32_e32 v139, v139
	v_add_f32_e32 v152, v136, v152
	v_exp_f32_e32 v140, v140
	v_add_f32_e32 v152, v137, v152
	v_exp_f32_e32 v141, v141
	v_add_f32_e32 v152, v138, v152
	v_exp_f32_e32 v142, v142
	v_add_f32_e32 v152, v139, v152
	v_exp_f32_e32 v143, v143
	v_add_f32_e32 v152, v140, v152
	v_add_f32_e32 v152, v141, v152
	v_add_f32_e32 v152, v142, v152
	v_add_f32_e32 v180, v143, v152
	v_cvt_pk_bf16_f32 v128, v128, v129
	v_cvt_pk_bf16_f32 v129, v130, v131
	v_cvt_pk_bf16_f32 v130, v132, v133
	v_cvt_pk_bf16_f32 v132, v136, v137
	v_cvt_pk_bf16_f32 v133, v138, v139
	v_add_u32_e32 v152, s0, v198
	ds_read_b128 v[136:139], v152 offset:0
	v_cvt_pk_bf16_f32 v131, v134, v135
	v_cvt_pk_bf16_f32 v134, v140, v141
	v_cvt_pk_bf16_f32 v135, v142, v143
	ds_read_b128 v[140:143], v152 offset:0x1000
.Lattn_exp_done_1_1:
	s_waitcnt lgkmcnt(1)
	v_or3_b32 v240, v128, v129, v130
	v_or3_b32 v240, v240, v131, v132
	v_or3_b32 v240, v240, v133, v134
	v_or3_b32 v240, v240, v135, v144
	v_or3_b32 v240, v240, v145, v146
	v_or3_b32 v240, v240, v147, v148
	v_or3_b32 v240, v240, v149, v150
	v_or_b32_e32 v240, v240, v151
	v_cmp_ne_u32_e32 vcc, 0, v240
	s_and_b64 vcc, exec, vcc
	s_cbranch_vccz .Lattn_pv_zero_1
	v_mfma_f32_32x32x16_bf16 v[112:127], v[136:139], v[144:147], v[112:127]
	v_mfma_f32_32x32x16_bf16 v[96:111], v[136:139], v[128:131], v[96:111]
	ds_read_b128 v[136:139], v152 offset:0x2000
	s_waitcnt lgkmcnt(1)
	v_mfma_f32_32x32x16_bf16 v[80:95], v[140:143], v[144:147], v[80:95]
	v_mfma_f32_32x32x16_bf16 v[64:79], v[140:143], v[128:131], v[64:79]
	ds_read_b128 v[140:143], v152 offset:0x3000
	s_waitcnt lgkmcnt(1)
	v_mfma_f32_32x32x16_bf16 v[48:63], v[136:139], v[144:147], v[48:63]
	v_mfma_f32_32x32x16_bf16 v[16:31], v[136:139], v[128:131], v[16:31]
	v_add_u32_e32 v152, s0, v199
	ds_read_b128 v[136:139], v152 offset:0
	s_waitcnt lgkmcnt(1)
	v_mfma_f32_32x32x16_bf16 v[32:47], v[140:143], v[144:147], v[32:47]
	v_mfma_f32_32x32x16_bf16 v[0:15], v[140:143], v[128:131], v[0:15]
	ds_read_b128 v[128:131], v152 offset:0x1000
	s_waitcnt lgkmcnt(1)
	v_mfma_f32_32x32x16_bf16 v[112:127], v[136:139], v[148:151], v[112:127]
	v_mfma_f32_32x32x16_bf16 v[96:111], v[136:139], v[132:135], v[96:111]
	ds_read_b128 v[136:139], v152 offset:0x2000
	s_waitcnt lgkmcnt(1)
	v_mfma_f32_32x32x16_bf16 v[80:95], v[128:131], v[148:151], v[80:95]
	v_mfma_f32_32x32x16_bf16 v[64:79], v[128:131], v[132:135], v[64:79]
	ds_read_b128 v[128:131], v152 offset:0x3000
	s_waitcnt lgkmcnt(1)
	v_mfma_f32_32x32x16_bf16 v[48:63], v[136:139], v[148:151], v[48:63]
	v_mfma_f32_32x32x16_bf16 v[16:31], v[136:139], v[132:135], v[16:31]
	s_waitcnt lgkmcnt(0)
	v_mfma_f32_32x32x16_bf16 v[32:47], v[128:131], v[148:151], v[32:47]
	v_mfma_f32_32x32x16_bf16 v[0:15], v[128:131], v[132:135], v[0:15]
